# v22 + pass prologue: tile-1 K/V loads issued right behind tile-0's (tile 0 via v80-95), no copies
# speedup vs baseline: 1.0317x; 1.0317x over previous
; template <int PM> DI void attn_phase(const Params& p, int l, char* smem, int* s_item, int wv, int cidx) {
;     ...
;       __syncthreads();
;       {
;         const u16* base = p.P + (size_t)(Rb + trow) * INW + tch * 8;
; #pragma unroll
;         for (int j = 0; j < 2; ++j) {
;           kst[j] = *(const u32x4*)(base + (size_t)j * 32 * INW + koff);
;           vst[j] = *(const u32x4*)(base + (size_t)j * 32 * INW + voff);
;         }
; #pragma unroll
;         for (int j = 0; j < 2; ++j) {
;           *(u32x4*)(Kb0 + (trow + 32 * j) * 272 + tch * 16) = kst[j];
;           *(u32x4*)(Vb0 + (trow + 32 * j) * 320 + tch * 16) = vst[j];
;         }
;         const int R1 = (1 < nplain) ? Rb + 64 : Rb + 256 + local_t0 + 64 * (1 - nplain);
;         const u16* b1 = p.P + (size_t)(R1 + trow) * INW + tch * 8;
;         if (ntl > 1) {
; #pragma unroll
;           for (int j = 0; j < 2; ++j) {
;             kst[j] = *(const u32x4*)(b1 + (size_t)j * 32 * INW + koff);
;             vst[j] = *(const u32x4*)(b1 + (size_t)j * 32 * INW + voff);
;           }
;         }
;       }
.LBB0_418:
	global_load_dwordx4 v[80:83], v[210:211], off
	global_load_dwordx4 v[84:87], v[212:213], off
	global_load_dwordx4 v[88:91], v[214:215], off
	global_load_dwordx4 v[92:95], v[216:217], off
	v_readlane_b32 s0, v255, 1
	v_readlane_b32 s1, v255, 2
	v_add_u32_e32 v0, v196, v246
	v_add_u32_e32 v2, v196, v247
	s_andn2_b64 vcc, exec, s[0:1]
	s_cbranch_vccnz .Lpq_one
	global_load_dwordx4 v[180:183], v[224:225], off
	global_load_dwordx4 v[184:187], v[222:223], off
	global_load_dwordx4 v[188:191], v[220:221], off
	global_load_dwordx4 v[192:195], v[218:219], off
	s_waitcnt lgkmcnt(0)
	s_barrier
	s_waitcnt vmcnt(7)
	ds_write_b128 v0, v[80:83]
	s_waitcnt vmcnt(6)
	ds_write_b128 v2, v[84:87] offset:34816
	s_waitcnt vmcnt(5)
	ds_write_b128 v0, v[88:91] offset:8704
	s_waitcnt vmcnt(4)
	ds_write_b128 v2, v[92:95] offset:45056
	s_branch .LBB0_420
.Lpq_one:
	s_waitcnt lgkmcnt(0)
	s_barrier
	s_waitcnt vmcnt(3)
	ds_write_b128 v0, v[80:83]
	s_waitcnt vmcnt(2)
	ds_write_b128 v2, v[84:87] offset:34816
	s_waitcnt vmcnt(1)
	ds_write_b128 v0, v[88:91] offset:8704
	s_waitcnt vmcnt(0)
	ds_write_b128 v2, v[92:95] offset:45056
